# fused retention-state step: the lane's two 8-byte state stores merged into one 16-byte store after a permlane16 row swap (vmcnt counts adjusted)
# baseline (speedup 1.0000x reference)
; #define LAS __attribute__((address_space(3)))
; __device__ __forceinline__ bf16_t f2bf(float f) { return (bf16_t)(pk2(f, 0.f) & 0xffffu); }
; __device__ __forceinline__ void refresh(Frame& F) { int t = threadIdx.x; asm volatile("" : "+v"(t)); F.tid = t; F.lane = t & 63; F.wave = __builtin_amdgcn_readfirstlane(t >> 6); }
; __device__ __forceinline__ void ret_state_item(const Args& A, Frame& F, int l, int it) {
;     refresh(F);
;     const int dvh = it & 1, dir = (it >> 1) & 1, h = (it >> 2) & 7, b = it >> 5;
;     const int lane = F.lane, fr = lane & 15, fq = lane >> 4, w = F.wave, dvt = w & 3, dkh = w >> 2;
;     const float l2g = log2_gamma(A, F, l, dir, h);
;     const float cdec = exp2f(128.f * l2g);
;     float dec[4][8];
; #pragma unroll
;     for (int ks = 0; ks < 4; ++ks)
; #pragma unroll
;         for (int s = 0; s < 8; ++s) { const int a = 32 * ks + 8 * fq + s; dec[ks][s] = exp2f(l2g * (float)(dir ? a : 127 - a)); }
;     const int dvrow = 64 * dvh + 16 * dvt + fr;
;     const bf16_t* kbase = WSB(WS_KT) + ((size_t)(b * NH + h) * DK + 32 * dkh + fr) * TB;
;     const bf16_t* vbase = WSB(WS_VT) + ((size_t)(b * NH + h) * DV + dvrow) * TB;
;     f32x4 acc[2];
;     acc[0] = (f32x4){0.f, 0.f, 0.f, 0.f}; acc[1] = acc[0];
;     bf16x8 ka[4][2], va[4], kb2[4][2], vb2[4];
; __device__ __forceinline__ void lru_item(const Args& A, Frame& F, int l, int it) {
;     refresh(F);
;     const int blk = it & 15, dir = (it >> 4) & 1, b = it >> 5;
;     const int tid = F.tid, lane = F.lane, fr = lane & 15, fq = lane >> 4, w = F.wave;
;     LAS float* us = (LAS float*)F.lds;
;     LAS float* as = us + 128 * 64;
;     LAS bf16_t* ub = (LAS bf16_t*)(F.lds + 65536);
;     LAS bf16_t* wgs = (LAS bf16_t*)(F.lds + 65536 + 18432);
;     LAS float* segA = (LAS float*)(F.lds + 65536 + 2 * 18432);
;     LAS float* segB = segA + 512;
;     LAS float* hcar = segA + 2048;
;     __syncthreads();
;     {
;         const float* gw = GIN(16) + ((size_t)(l * 2 + dir) * 2) * 16 * 64 * 64;
;         for (int e = tid; e < 2 * 64 * 64; e += NTHREADS) {
;             const int g = e >> 12, k = (e >> 6) & 63, j = e & 63;
;             wgs[(g * 64 + j) * 72 + k] = f2bf(gw[((size_t)(g * 16 + blk) * 64 + k) * 64 + j]);
;         }
;         if (tid < 128) hcar[tid] = 0.f;
;     }
.LBB0_51:
	v_readfirstlane_b32 s2, v138
	s_and_b32 s8, s37, 1
	s_bfe_u32 s10, s37, 0x10001
	s_lshr_b32 s9, s37, 2
	s_and_b32 s12, s9, 7
	s_lshr_b32 s2, s2, 6
	s_lshl_b32 s13, s10, 3
	s_add_i32 s13, s13, s12
	s_add_i32 s13, s13, s53
	s_lshl_b32 s13, s13, 2
	s_load_dwordx2 s[100:101], s[46:47], 0x60
	s_waitcnt lgkmcnt(0)
	s_load_dword s5, s[100:101], s13
	s_lshr_b32 s15, s2, 2
	s_and_b32 s18, s2, 3
	s_cmp_eq_u32 s10, 0
	s_cselect_b32 s14, -1, 1
	s_waitcnt lgkmcnt(0)
	v_mov_b32_e32 v250, s5
	v_and_b32_e32 v251, 0x7fffffff, v250
	v_mul_f32_e32 v251, 0xbfb8aa3b, v251
	v_exp_f32_e32 v251, v251
	v_mov_b32_e32 v252, 0x3e4ccccd
	v_fmaak_f32 v252, v251, v252, 0xbe800000
	v_fmaak_f32 v252, v251, v252, 0x3eaaaaab
	v_fmaak_f32 v252, v251, v252, 0xbf000000
	v_fmaak_f32 v252, v251, v252, 0x3f800000
	v_mul_f32_e32 v252, v251, v252
	v_add_f32_e32 v253, 1.0, v251
	v_log_f32_e32 v253, v253
	v_cmp_gt_f32_e32 vcc, 0x3c800000, v251
	v_mul_f32_e32 v253, 0x3f317218, v253
	s_nop 1
	v_cndmask_b32_e32 v252, v253, v252, vcc
	v_max_f32_e64 v253, -v250, 0
	v_add_f32_e32 v252, v253, v252
	v_mul_f32_e32 v252, 0xbfb8aa3b, v252
	v_mul_f32_e32 v168, 0x43000000, v252
	v_exp_f32_e32 v168, v168
	v_and_b32_e32 v141, 63, v138
	v_and_b32_e32 v137, 15, v141
	v_lshrrev_b32_e32 v141, 4, v141
	s_cmp_eq_u32 s10, 0
	s_cselect_b32 s4, 0x7f, 0
	v_mov_b32_e32 v143, s14
	v_lshlrev_b32_e32 v255, 3, v141
	v_mad_i32_i24 v255, v143, v255, s4
	v_mad_i32_i24 v250, v143, 0, v255
	v_cvt_f32_i32_e32 v250, v250
	v_mul_f32_e32 v250, v252, v250
	v_exp_f32_e32 v152, v250
	v_mad_i32_i24 v250, v143, 1, v255
	v_cvt_f32_i32_e32 v250, v250
	v_mul_f32_e32 v250, v252, v250
	v_exp_f32_e32 v153, v250
	v_mad_i32_i24 v250, v143, 2, v255
	v_cvt_f32_i32_e32 v250, v250
	v_mul_f32_e32 v250, v252, v250
	v_exp_f32_e32 v154, v250
	v_mad_i32_i24 v250, v143, 3, v255
	v_cvt_f32_i32_e32 v250, v250
	v_mul_f32_e32 v250, v252, v250
	v_exp_f32_e32 v155, v250
	v_mad_i32_i24 v250, v143, 4, v255
	v_cvt_f32_i32_e32 v250, v250
	v_mul_f32_e32 v250, v252, v250
	v_exp_f32_e32 v156, v250
	v_mad_i32_i24 v250, v143, 5, v255
	v_cvt_f32_i32_e32 v250, v250
	v_mul_f32_e32 v250, v252, v250
	v_exp_f32_e32 v157, v250
	v_mad_i32_i24 v250, v143, 6, v255
	v_cvt_f32_i32_e32 v250, v250
	v_mul_f32_e32 v250, v252, v250
	v_exp_f32_e32 v158, v250
	v_mad_i32_i24 v250, v143, 7, v255
	v_cvt_f32_i32_e32 v250, v250
	v_mul_f32_e32 v250, v252, v250
	v_exp_f32_e32 v159, v250
	s_lshl_b32 s4, s14, 5
	v_cvt_f32_i32_e32 v250, s4
	v_mul_f32_e32 v250, v252, v250
	v_add_f32_e32 v251, v250, v250
	v_add_f32_e32 v253, v251, v250
	v_exp_f32_e32 v244, v250
	v_exp_f32_e32 v246, v251
	v_exp_f32_e32 v248, v253
	s_lshl_b32 s4, s9, 6
	s_lshl_b32 s5, s15, 5
	s_add_i32 s4, s4, s5
	s_mulk_i32 s4, 0x1200
	v_mul_u32_u24_e32 v169, 0x1200, v137
	v_lshl_add_u32 v169, v141, 4, v169
	v_add_u32_e32 v169, s4, v169
	s_lshl_b32 s5, s8, 6
	s_lshl_b32 s18, s18, 4
	s_add_i32 s18, s18, s5
	s_lshl_b32 s4, s9, 7
	s_add_i32 s4, s4, s18
	s_mulk_i32 s4, 0x1200
	v_mul_u32_u24_e32 v242, 0x1200, v137
	v_lshl_add_u32 v242, v141, 4, v242
	v_add_u32_e32 v242, s4, v242
	s_lshl_b32 s4, s9, 1
	s_add_i32 s4, s4, s10
	s_mulk_i32 s4, 0x900
	s_add_i32 s4, s4, s18
	s_lshl_b32 s4, s4, 7
	s_lshl_b32 s5, s15, 6
	s_add_i32 s4, s4, s5
	v_lshlrev_b32_e32 v243, 7, v137
	v_lshl_add_u32 v243, v141, 3, v243
	v_add_u32_e32 v243, s4, v243
	v_and_b32_e32 v250, 1, v141
	v_mul_u32_u24_e32 v250, 24, v250
	v_add_u32_e32 v243, v243, v250
	v_mov_b32_e32 v160, 0
	v_mov_b32_e32 v161, 0
	v_mov_b32_e32 v162, 0
	v_mov_b32_e32 v163, 0
	v_mov_b32_e32 v164, 0
	v_mov_b32_e32 v165, 0
	v_mov_b32_e32 v166, 0
	v_mov_b32_e32 v167, 0
	s_bfe_u32 s45, s37, 0x10004
	v_mov_b32_e32 v54, v138
	s_or_b32 s4, s45, s85
	s_movk_i32 s8, 0x2000
	s_and_b32 s39, s37, 15
	v_and_b32_e32 v102, 63, v54
	v_readfirstlane_b32 s2, v54
	s_ashr_i32 s5, s4, 31
	v_cmp_gt_i32_e32 vcc, s8, v54
	s_barrier
	s_and_saveexec_b64 s[8:9], vcc
	s_mov_b32 s18, 0x33800000
	s_mov_b32 s19, 0x3f317218
	s_cbranch_execz .LBB0_59
	s_load_dwordx2 s[10:11], s[46:47], 0x80
	s_lshl_b64 s[12:13], s[4:5], 19
	v_lshrrev_b32_e32 v141, 6, v54
	v_lshlrev_b32_e32 v137, 8, v141
	v_lshl_add_u32 v137, v102, 2, v137
	v_mul_u32_u24_e32 v0, 0x90, v102
	v_lshl_add_u32 v141, v141, 1, v0
	v_add_u32_e32 v141, 0x14800, v141
	s_waitcnt lgkmcnt(0)
	s_add_u32 s10, s10, s12
	s_addc_u32 s11, s11, s13
	s_lshl_b32 s12, s39, 14
	s_add_u32 s10, s10, s12
	s_addc_u32 s11, s11, 0
	s_waitcnt vmcnt(0)
	global_load_dword v2, v137, s[10:11]
	s_add_u32 s100, s10, 0x800
	s_addc_u32 s101, s11, 0
	global_load_dword v3, v137, s[100:101]
	s_add_u32 s98, s10, 0x1000
	s_addc_u32 s99, s11, 0
	global_load_dword v4, v137, s[98:99]
	s_add_u32 s100, s10, 0x1800
	s_addc_u32 s101, s11, 0
	global_load_dword v5, v137, s[100:101]
	s_add_u32 s98, s10, 0x2000
	s_addc_u32 s99, s11, 0
	global_load_dword v6, v137, s[98:99]
	s_add_u32 s100, s10, 0x2800
	s_addc_u32 s101, s11, 0
	global_load_dword v7, v137, s[100:101]
	s_add_u32 s98, s10, 0x3000
	s_addc_u32 s99, s11, 0
	global_load_dword v8, v137, s[98:99]
	s_add_u32 s100, s10, 0x3800
	s_addc_u32 s101, s11, 0
	global_load_dword v9, v137, s[100:101]
	s_add_u32 s98, s10, 0x40000
	s_addc_u32 s99, s11, 0
	global_load_dword v10, v137, s[98:99]
	s_add_u32 s100, s10, 0x40800
	s_addc_u32 s101, s11, 0
	global_load_dword v11, v137, s[100:101]
	s_add_u32 s98, s10, 0x41000
	s_addc_u32 s99, s11, 0
	global_load_dword v12, v137, s[98:99]
	s_add_u32 s100, s10, 0x41800
	s_addc_u32 s101, s11, 0
	global_load_dword v13, v137, s[100:101]
	s_add_u32 s98, s10, 0x42000
	s_addc_u32 s99, s11, 0
	global_load_dword v14, v137, s[98:99]
	s_add_u32 s100, s10, 0x42800
	s_addc_u32 s101, s11, 0
	global_load_dword v15, v137, s[100:101]
	s_add_u32 s98, s10, 0x43000
	s_addc_u32 s99, s11, 0
	global_load_dword v143, v137, s[98:99]
	s_add_u32 s100, s10, 0x43800
	s_addc_u32 s101, s11, 0
	global_load_dword v255, v137, s[100:101]
	s_waitcnt vmcnt(14)
	v_cvt_pk_bf16_f32 v2, v2, v3
	ds_write_b16 v141, v2
	ds_write_b16_d16_hi v141, v2 offset:16
	s_waitcnt vmcnt(12)
	v_cvt_pk_bf16_f32 v4, v4, v5
	ds_write_b16 v141, v4 offset:32
	ds_write_b16_d16_hi v141, v4 offset:48
	s_waitcnt vmcnt(10)
	v_cvt_pk_bf16_f32 v6, v6, v7
	ds_write_b16 v141, v6 offset:64
	ds_write_b16_d16_hi v141, v6 offset:80
	s_waitcnt vmcnt(8)
	v_cvt_pk_bf16_f32 v8, v8, v9
	ds_write_b16 v141, v8 offset:96
	ds_write_b16_d16_hi v141, v8 offset:112
	s_waitcnt vmcnt(6)
	v_cvt_pk_bf16_f32 v10, v10, v11
	ds_write_b16 v141, v10 offset:9216
	ds_write_b16_d16_hi v141, v10 offset:9232
	s_waitcnt vmcnt(4)
	v_cvt_pk_bf16_f32 v12, v12, v13
	ds_write_b16 v141, v12 offset:9248
	ds_write_b16_d16_hi v141, v12 offset:9264
	s_waitcnt vmcnt(2)
	v_cvt_pk_bf16_f32 v14, v14, v15
	ds_write_b16 v141, v14 offset:9280
	ds_write_b16_d16_hi v141, v14 offset:9296
	s_waitcnt vmcnt(0)
	v_cvt_pk_bf16_f32 v143, v143, v255
	ds_write_b16 v141, v143 offset:9312
	ds_write_b16_d16_hi v141, v143 offset:9328
	s_mov_b32 s53, s64

; #define LAS __attribute__((address_space(3)))
; __device__ __forceinline__ unsigned pk2(float lo, float hi) { const f32x2_t v = {lo, hi}; const bf16v2_t b = __builtin_convertvector(v, bf16v2_t); return __builtin_bit_cast(unsigned, b); }
; __device__ __forceinline__ float bflo(unsigned u) { return __uint_as_float(u << 16); }
; __device__ __forceinline__ float bfhi(unsigned u) { return __uint_as_float(u & 0xffff0000u); }
; __device__ __forceinline__ void lru_item(const Args& A, Frame& F, int l, int it) {
;     ...
;     for (int sc = 0; sc < NCH; ++sc) {
;         const int lo = sc < 2 ? 0 : CTXL, hi = sc < 2 ? CTXL : TB;
;         const int pbase = dir == 0 ? 128 * sc : (sc < 2 ? 255 - 128 * sc : 2303 - 128 * (sc - 2));
;         {
;             const int pmin = dir == 0 ? pbase + 4 * g4 : pbase - 4 * g4 - 3;
;             f32x4 xw[7];
; #pragma unroll
;             for (int e = 0; e < 7; ++e) {
;                 const int q = pmin - 2 + e;
;                 const float msk = (q >= lo && q < hi) ? 1.f : 0.f;
;                 xw[e][0] = bflo(xr[e].x) * msk; xw[e][1] = bfhi(xr[e].x) * msk; xw[e][2] = bflo(xr[e].y) * msk; xw[e][3] = bfhi(xr[e].y) * msk;
;             }
; #pragma unroll
;             for (int m = 0; m < 4; ++m) {
;                 const f32x4 a = cb + cw[0] * xw[m] + cw[1] * xw[m + 1] + cw[2] * xw[m + 2] + cw[3] * xw[m + 3];
;                 const int si = dir == 0 ? 4 * g4 + m : 4 * g4 + 3 - m;
;                 *(LAS f32x4*)(us + si * 64 + c4) = a;
;                 u32x2 o; o.x = pk2(a[0], a[1]); o.y = pk2(a[2], a[3]);
;                 *(LAS u32x2*)(ub + si * 72 + c4) = o;
;             }
;         }
;         {
;             const int sn = sc + 1 < NCH ? sc + 1 : sc;
;             const int lon = sn < 2 ? 0 : CTXL, hin = sn < 2 ? CTXL : TB;
;             const int pbn = dir == 0 ? 128 * sn : (sn < 2 ? 255 - 128 * sn : 2303 - 128 * (sn - 2));
;             const int pminn = dir == 0 ? pbn + 4 * g4 : pbn - 4 * g4 - 3;
; #pragma unroll
;             for (int e = 0; e < 7; ++e) { const int q = pminn - 2 + e; const int qc = q < lon ? lon : (q >= hin ? hin - 1 : q); xr[e] = *(const u32x2*)(lx + (size_t)qc * D); }
;         }
.LBB0_70:
	v_sub_u32_e32 v24, s39, v88
	s_and_b64 s[4:5], s[4:5], exec
	v_add_u32_e32 v23, s39, v88
	v_add_u32_e32 v24, -3, v24
	s_movk_i32 s4, 0x100
	v_cndmask_b32_e64 v23, v24, v23, s[8:9]
	s_cselect_b32 s25, 0, 0x100
	s_cselect_b32 s52, s4, 0x900
	v_add_u32_e32 v24, -2, v23
	v_cmp_le_i32_e32 vcc, s25, v24
	v_cmp_gt_i32_e64 s[14:15], s52, v24
	s_and_b64 s[4:5], vcc, s[14:15]
	v_cmp_lt_i32_e32 vcc, s25, v23
	v_cmp_ge_i32_e64 s[14:15], s52, v23
	v_cndmask_b32_e64 v24, 0, 1.0, s[4:5]
	s_waitcnt vmcnt(35)
	v_lshlrev_b32_e32 v26, 16, v62
	v_and_b32_e32 v27, 0xffff0000, v62
	v_lshlrev_b32_e32 v28, 16, v63
	v_and_b32_e32 v29, 0xffff0000, v63
	s_and_b64 s[4:5], vcc, s[14:15]
	v_cmp_le_i32_e32 vcc, s25, v23
	v_cmp_gt_i32_e64 s[14:15], s52, v23
	v_pk_mul_f32 v[26:27], v[24:25], v[26:27] op_sel_hi:[0,1]
	v_pk_mul_f32 v[24:25], v[24:25], v[28:29] op_sel_hi:[0,1]
	v_cndmask_b32_e64 v28, 0, 1.0, s[4:5]
	s_waitcnt vmcnt(34)
	v_lshlrev_b32_e32 v30, 16, v64
	v_and_b32_e32 v31, 0xffff0000, v64
	v_lshlrev_b32_e32 v32, 16, v65
	v_and_b32_e32 v33, 0xffff0000, v65
	s_and_b64 s[4:5], vcc, s[14:15]
	v_pk_mul_f32 v[30:31], v[28:29], v[30:31] op_sel_hi:[0,1]
	v_pk_mul_f32 v[28:29], v[28:29], v[32:33] op_sel_hi:[0,1]
	v_cndmask_b32_e64 v32, 0, 1.0, s[4:5]
	s_waitcnt vmcnt(33)
	v_lshlrev_b32_e32 v34, 16, v66
	v_and_b32_e32 v35, 0xffff0000, v66
	v_lshlrev_b32_e32 v36, 16, v67
	v_and_b32_e32 v37, 0xffff0000, v67
	v_pk_mul_f32 v[34:35], v[32:33], v[34:35] op_sel_hi:[0,1]
	v_pk_mul_f32 v[32:33], v[32:33], v[36:37] op_sel_hi:[0,1]
	v_add_u32_e32 v36, 1, v23
	v_cmp_le_i32_e32 vcc, s25, v36
	v_cmp_gt_i32_e64 s[14:15], s52, v36
	s_and_b64 s[4:5], vcc, s[14:15]
	v_cndmask_b32_e64 v36, 0, 1.0, s[4:5]
	s_waitcnt vmcnt(32)
	v_lshlrev_b32_e32 v38, 16, v68
	v_and_b32_e32 v39, 0xffff0000, v68
	v_lshlrev_b32_e32 v40, 16, v69
	v_and_b32_e32 v41, 0xffff0000, v69
	v_pk_mul_f32 v[38:39], v[36:37], v[38:39] op_sel_hi:[0,1]
	v_pk_mul_f32 v[36:37], v[36:37], v[40:41] op_sel_hi:[0,1]
	v_add_u32_e32 v40, 2, v23
	v_cmp_le_i32_e32 vcc, s25, v40
	v_cmp_gt_i32_e64 s[14:15], s52, v40
	s_and_b64 s[4:5], vcc, s[14:15]
	v_cndmask_b32_e64 v40, 0, 1.0, s[4:5]
	s_waitcnt vmcnt(31)
	v_lshlrev_b32_e32 v42, 16, v70
	v_and_b32_e32 v43, 0xffff0000, v70
	v_lshlrev_b32_e32 v44, 16, v71
	v_and_b32_e32 v45, 0xffff0000, v71
	v_pk_mul_f32 v[42:43], v[40:41], v[42:43] op_sel_hi:[0,1]
	v_pk_mul_f32 v[40:41], v[40:41], v[44:45] op_sel_hi:[0,1]
	v_add_u32_e32 v44, 3, v23
	v_cmp_le_i32_e32 vcc, s25, v44
	v_cmp_gt_i32_e64 s[14:15], s52, v44
	v_add_u32_e32 v23, 4, v23
	s_and_b64 s[4:5], vcc, s[14:15]
	v_cmp_le_i32_e32 vcc, s25, v23
	v_cmp_gt_i32_e64 s[14:15], s52, v23
	v_cndmask_b32_e64 v44, 0, 1.0, s[4:5]
	s_waitcnt vmcnt(30)
	v_lshlrev_b32_e32 v46, 16, v72
	v_and_b32_e32 v47, 0xffff0000, v72
	v_lshlrev_b32_e32 v48, 16, v73
	v_and_b32_e32 v49, 0xffff0000, v73
	s_and_b64 s[4:5], vcc, s[14:15]
	v_pk_fma_f32 v[26:27], v[2:3], v[26:27], v[18:19]
	v_pk_fma_f32 v[24:25], v[4:5], v[24:25], v[20:21]
	v_pk_mul_f32 v[46:47], v[44:45], v[46:47] op_sel_hi:[0,1]
	v_pk_mul_f32 v[44:45], v[44:45], v[48:49] op_sel_hi:[0,1]
	v_cndmask_b32_e64 v48, 0, 1.0, s[4:5]
	s_waitcnt vmcnt(29)
	v_lshlrev_b32_e32 v50, 16, v74
	v_and_b32_e32 v51, 0xffff0000, v74
	v_lshlrev_b32_e32 v52, 16, v75
	v_and_b32_e32 v53, 0xffff0000, v75
	v_pk_fma_f32 v[24:25], v[8:9], v[28:29], v[24:25]
	v_pk_fma_f32 v[26:27], v[6:7], v[30:31], v[26:27]
	v_pk_mul_f32 v[50:51], v[48:49], v[50:51] op_sel_hi:[0,1]
	v_pk_mul_f32 v[48:49], v[48:49], v[52:53] op_sel_hi:[0,1]
	v_pk_fma_f32 v[52:53], v[10:11], v[34:35], v[26:27]
	v_pk_fma_f32 v[24:25], v[12:13], v[32:33], v[24:25]
	v_lshl_add_u32 v23, v22, 8, v89
	v_pk_fma_f32 v[26:27], v[16:17], v[36:37], v[24:25]
	v_pk_fma_f32 v[24:25], v[14:15], v[38:39], v[52:53]
	ds_write_b128 v23, v[24:27]
	v_cvt_pk_bf16_f32 v24, v24, v25
	v_cvt_pk_bf16_f32 v25, v26, v27
	v_mad_u64_u32 v[22:23], s[4:5], v22, s97, v[58:59]
	ds_write_b64 v22, v[24:25]
	v_pk_fma_f32 v[22:23], v[2:3], v[30:31], v[18:19]
	v_pk_fma_f32 v[24:25], v[4:5], v[28:29], v[20:21]
	v_pk_fma_f32 v[22:23], v[6:7], v[34:35], v[22:23]
	v_pk_fma_f32 v[24:25], v[8:9], v[32:33], v[24:25]
	v_pk_fma_f32 v[22:23], v[10:11], v[38:39], v[22:23]
	v_pk_fma_f32 v[24:25], v[12:13], v[36:37], v[24:25]
	v_pk_fma_f32 v[22:23], v[14:15], v[42:43], v[22:23]
	v_pk_fma_f32 v[24:25], v[16:17], v[40:41], v[24:25]
	ds_write_b128 v130, v[22:25]
	v_cvt_pk_bf16_f32 v22, v22, v23
	v_cvt_pk_bf16_f32 v23, v24, v25
	ds_write_b64 v131, v[22:23]
	v_pk_fma_f32 v[22:23], v[2:3], v[34:35], v[18:19]
	v_pk_fma_f32 v[24:25], v[4:5], v[32:33], v[20:21]
	v_pk_fma_f32 v[22:23], v[6:7], v[38:39], v[22:23]
	v_pk_fma_f32 v[24:25], v[8:9], v[36:37], v[24:25]
	v_pk_fma_f32 v[22:23], v[10:11], v[42:43], v[22:23]
	v_pk_fma_f32 v[24:25], v[12:13], v[40:41], v[24:25]
	v_pk_fma_f32 v[22:23], v[14:15], v[46:47], v[22:23]
	v_pk_fma_f32 v[24:25], v[16:17], v[44:45], v[24:25]
	ds_write_b128 v132, v[22:25]
	v_cvt_pk_bf16_f32 v22, v22, v23
	v_cvt_pk_bf16_f32 v23, v24, v25
	ds_write_b64 v133, v[22:23]
	v_pk_fma_f32 v[22:23], v[2:3], v[38:39], v[18:19]
	v_pk_fma_f32 v[24:25], v[4:5], v[36:37], v[20:21]
	v_pk_fma_f32 v[22:23], v[6:7], v[42:43], v[22:23]
	v_pk_fma_f32 v[24:25], v[8:9], v[40:41], v[24:25]
	v_pk_fma_f32 v[22:23], v[10:11], v[46:47], v[22:23]
	v_pk_fma_f32 v[24:25], v[12:13], v[44:45], v[24:25]
	v_or_b32_e32 v26, s45, v88
	v_pk_fma_f32 v[24:25], v[16:17], v[48:49], v[24:25]
	v_pk_fma_f32 v[22:23], v[14:15], v[50:51], v[22:23]
	v_lshl_add_u32 v27, v26, 8, v89
	s_add_i32 s45, s2, 1
	ds_write_b128 v27, v[22:25]
	v_cvt_pk_bf16_f32 v22, v22, v23
	v_cvt_pk_bf16_f32 v23, v24, v25
	v_mad_u64_u32 v[24:25], s[4:5], v26, s97, v[58:59]
; #define LAS __attribute__((address_space(3)))
; __device__ __forceinline__ void lru_item(const Args& A, Frame& F, int l, int it) {
;     ...
;         {
;             const int sn = sc + 1 < NCH ? sc + 1 : sc;
;             const int lon = sn < 2 ? 0 : CTXL, hin = sn < 2 ? CTXL : TB;
;             const int pbn = dir == 0 ? 128 * sn : (sn < 2 ? 255 - 128 * sn : 2303 - 128 * (sn - 2));
;             const int pminn = dir == 0 ? pbn + 4 * g4 : pbn - 4 * g4 - 3;
; #pragma unroll
;             for (int e = 0; e < 7; ++e) { const int q = pminn - 2 + e; const int qc = q < lon ? lon : (q >= hin ? hin - 1 : q); xr[e] = *(const u32x2*)(lx + (size_t)qc * D); }
;         }
;         __builtin_amdgcn_fence(__ATOMIC_RELEASE, "workgroup"); __builtin_amdgcn_wave_barrier(); __builtin_amdgcn_fence(__ATOMIC_ACQUIRE, "workgroup");
;         {
;             bf16x8 af[2];
; #pragma unroll
;             for (int ks = 0; ks < 2; ++ks) af[ks] = *(const LAS bf16x8*)(ub + (16 * w + fr) * 72 + 32 * ks + 8 * fq);
;             f32x4 gacc[8];
; #pragma unroll
;             for (int nt = 0; nt < 8; ++nt) {
;                 gacc[nt] = (f32x4){0.f, 0.f, 0.f, 0.f};
; #pragma unroll
;                 for (int ks = 0; ks < 2; ++ks) {
;                     const bf16x8 bfm = *(const LAS bf16x8*)(wgs + (16 * nt + fr) * 72 + 32 * ks + 8 * fq);
;                     gacc[nt] = __builtin_amdgcn_mfma_f32_16x16x32_bf16(af[ks], bfm, gacc[nt], 0, 0, 0);
;                 }
;             }
; #pragma unroll
;             for (int nt = 0; nt < 4; ++nt)
; #pragma unroll
;                 for (int r = 0; r < 4; ++r) {
;                     const int si = 16 * w + 4 * fq + r, ch = 16 * nt + fr;
;                     const float d0 = 1.f + __builtin_amdgcn_exp2f(fminf((gacc[nt][r] + bgr[nt]) * -1.4426950408889634f, 60.f));
;                     const float d1 = 1.f + __builtin_amdgcn_exp2f(fminf((gacc[nt + 4][r] + bgi[nt]) * -1.4426950408889634f, 60.f));
;                     const float rr = frcp(d0 * d1);
;                     const float rg = rr * d1, ig = rr * d0;
;                     const float av = __builtin_amdgcn_exp2f(rg * spl[nt]);
;                     const float mult = __builtin_amdgcn_sqrtf(fmaxf(1.f - av * av, 0.f));
;                     const float uu = us[si * 64 + ch];
;                     as[si * 64 + ch] = av;
;                     us[si * 64 + ch] = mult * ig * uu;
;                 }
	s_cmp_lg_u32 s2, 17
	s_cselect_b32 s4, s45, 17
	s_lshl_b32 s14, s4, 7
	s_sub_i32 s5, 0x9ff, s14
	s_cmp_lt_u32 s4, 2
	s_movk_i32 s4, 0x8ff
	s_cselect_b32 s15, 0, 0x100
	s_cselect_b32 s25, 0x7f, s5
	s_cselect_b32 s52, 0xff, s4
	s_and_b64 s[4:5], s[8:9], exec
	s_cselect_b32 s4, s14, s25
	ds_write_b64 v24, v[22:23]
	v_sub_u32_e32 v23, s4, v88
	v_add_u32_e32 v22, s14, v88
	v_add_u32_e32 v23, -3, v23
	v_cndmask_b32_e64 v24, v23, v22, s[8:9]
	v_add_u32_e32 v22, -2, v24
	v_cmp_gt_i32_e32 vcc, s15, v22
	v_min_i32_e32 v22, s52, v22
	v_mov_b32_e32 v25, s15
	v_cndmask_b32_e32 v22, v22, v25, vcc
	v_ashrrev_i32_e32 v23, 31, v22
	v_lshlrev_b64 v[22:23], 11, v[22:23]
	v_lshl_add_u64 v[22:23], v[56:57], 0, v[22:23]
	global_load_dwordx2 v[62:63], v[22:23], off
	v_add_u32_e32 v22, -1, v24
	v_cmp_lt_i32_e32 vcc, s15, v24
	v_min_i32_e32 v22, s52, v22
	s_and_b32 s2, s2, 1
	v_cndmask_b32_e32 v22, v25, v22, vcc
	v_ashrrev_i32_e32 v23, 31, v22
	v_lshlrev_b64 v[22:23], 11, v[22:23]
	v_lshl_add_u64 v[22:23], v[56:57], 0, v[22:23]
	global_load_dwordx2 v[64:65], v[22:23], off
	v_cmp_gt_i32_e32 vcc, s15, v24
	v_min_i32_e32 v22, s52, v24
	s_lshl_b32 s4, s2, 12
	v_cndmask_b32_e32 v22, v22, v25, vcc
	v_ashrrev_i32_e32 v23, 31, v22
	v_lshlrev_b64 v[22:23], 11, v[22:23]
	v_lshl_add_u64 v[22:23], v[56:57], 0, v[22:23]
	global_load_dwordx2 v[66:67], v[22:23], off
	v_add_u32_e32 v22, 1, v24
	v_cmp_gt_i32_e32 vcc, s15, v22
	v_min_i32_e32 v22, s52, v22
	s_add_i32 s4, s4, 0
	v_cndmask_b32_e32 v22, v22, v25, vcc
	v_ashrrev_i32_e32 v23, 31, v22
	v_lshlrev_b64 v[22:23], 11, v[22:23]
	v_lshl_add_u64 v[22:23], v[56:57], 0, v[22:23]
	global_load_dwordx2 v[68:69], v[22:23], off
	v_add_u32_e32 v22, 2, v24
	v_cmp_gt_i32_e32 vcc, s15, v22
	v_min_i32_e32 v22, s52, v22
	s_nop 0
	v_cndmask_b32_e32 v22, v22, v25, vcc
	v_ashrrev_i32_e32 v23, 31, v22
	v_lshlrev_b64 v[22:23], 11, v[22:23]
	v_lshl_add_u64 v[22:23], v[56:57], 0, v[22:23]
	global_load_dwordx2 v[70:71], v[22:23], off
	v_add_u32_e32 v22, 3, v24
	v_cmp_gt_i32_e32 vcc, s15, v22
	v_min_i32_e32 v22, s52, v22
	s_nop 0
	v_cndmask_b32_e32 v22, v22, v25, vcc
	v_ashrrev_i32_e32 v23, 31, v22
	v_lshlrev_b64 v[22:23], 11, v[22:23]
	v_lshl_add_u64 v[22:23], v[56:57], 0, v[22:23]
	global_load_dwordx2 v[72:73], v[22:23], off
	v_add_u32_e32 v22, 4, v24
	v_cmp_gt_i32_e32 vcc, s15, v22
	v_min_i32_e32 v22, s52, v22
	s_nop 0
	v_cndmask_b32_e32 v22, v22, v25, vcc
	v_ashrrev_i32_e32 v23, 31, v22
	v_lshlrev_b64 v[22:23], 11, v[22:23]
	v_lshl_add_u64 v[22:23], v[56:57], 0, v[22:23]
	global_load_dwordx2 v[74:75], v[22:23], off
	s_waitcnt lgkmcnt(0)
	ds_read_b128 v[26:29], v134
	ds_read_b128 v[144:147], v134 offset:64
	ds_read_b128 v[22:25], v135
	ds_read_b128 v[30:33], v135 offset:64
	ds_read_b128 v[34:37], v135 offset:6976
	s_waitcnt lgkmcnt(2)
	v_mfma_f32_16x16x32_bf16 v[22:25], v[26:29], v[22:25], 0
	ds_read_b128 v[42:45], v135 offset:9280
	ds_read_b128 v[148:151], v135 offset:13888
	s_waitcnt lgkmcnt(3)
	v_mfma_f32_16x16x32_bf16 v[46:49], v[144:147], v[30:33], v[22:25]
	ds_read_b128 v[30:33], v135 offset:2368
	s_nop 2
	ds_read_b128 v[22:25], v135 offset:2304
	s_waitcnt lgkmcnt(0)
	v_mfma_f32_16x16x32_bf16 v[22:25], v[26:29], v[22:25], 0
	s_nop 0
	v_add_f32_e32 v46, v55, v46
	v_mul_f32_e32 v46, 0xbfb8aa3b, v46
	v_min_f32_e32 v46, 0x42700000, v46
	v_mfma_f32_16x16x32_bf16 v[38:41], v[144:147], v[30:33], v[22:25]
	ds_read_b128 v[30:33], v135 offset:4672
	v_exp_f32_e32 v46, v46
	v_add_f32_e32 v48, v55, v48
	ds_read_b128 v[22:25], v135 offset:4608
	s_waitcnt lgkmcnt(0)
	v_mfma_f32_16x16x32_bf16 v[22:25], v[26:29], v[22:25], 0
	v_add_f32_e32 v46, 1.0, v46
	v_mul_f32_e32 v48, 0xbfb8aa3b, v48
	v_min_f32_e32 v48, 0x42700000, v48
	v_mfma_f32_16x16x32_bf16 v[30:33], v[144:147], v[30:33], v[22:25]
	v_exp_f32_e32 v48, v48
	v_add_f32_e32 v38, v59, v38
	v_mul_f32_e32 v38, 0xbfb8aa3b, v38
	s_nop 0
	ds_read_b128 v[22:25], v135 offset:6912
	s_waitcnt lgkmcnt(0)
	v_mfma_f32_16x16x32_bf16 v[22:25], v[26:29], v[22:25], 0
	v_add_f32_e32 v48, 1.0, v48
	v_min_f32_e32 v38, 0x42700000, v38
	v_exp_f32_e32 v38, v38
	v_mfma_f32_16x16x32_bf16 v[22:25], v[144:147], v[34:37], v[22:25]
	ds_read_b128 v[34:37], v135 offset:9216
	v_add_f32_e32 v40, v59, v40
	v_add_f32_e32 v38, 1.0, v38
	s_waitcnt lgkmcnt(0)
	v_mfma_f32_16x16x32_bf16 v[34:37], v[26:29], v[34:37], 0
	v_mul_f32_e32 v40, 0xbfb8aa3b, v40
	v_min_f32_e32 v40, 0x42700000, v40
	v_exp_f32_e32 v40, v40
	v_mfma_f32_16x16x32_bf16 v[50:53], v[144:147], v[42:45], v[34:37]
	ds_read_b128 v[42:45], v135 offset:11584
	v_add_f32_e32 v30, v78, v30
	v_add_f32_e32 v40, 1.0, v40
	s_nop 0
	ds_read_b128 v[34:37], v135 offset:11520
	s_waitcnt lgkmcnt(0)
	v_mfma_f32_16x16x32_bf16 v[34:37], v[26:29], v[34:37], 0
	s_nop 0
	v_add_f32_e32 v50, v83, v50
	v_mul_f32_e32 v50, 0xbfb8aa3b, v50
	v_min_f32_e32 v50, 0x42700000, v50
	v_exp_f32_e32 v50, v50
	v_mfma_f32_16x16x32_bf16 v[42:45], v[144:147], v[42:45], v[34:37]
	v_mul_f32_e32 v30, 0xbfb8aa3b, v30
	v_min_f32_e32 v30, 0x42700000, v30
	v_add_f32_e32 v50, 1.0, v50
	v_mul_f32_e32 v76, v46, v50
	v_rcp_f32_e32 v76, v76
	ds_read_b128 v[34:37], v135 offset:13824
	s_waitcnt lgkmcnt(0)
	v_mfma_f32_16x16x32_bf16 v[34:37], v[26:29], v[34:37], 0
	v_mul_f32_e32 v50, v50, v76
	v_mul_f32_e32 v50, v80, v50
	v_exp_f32_e32 v50, v50
	v_mul_f32_e32 v46, v46, v76
	v_mfma_f32_16x16x32_bf16 v[34:37], v[144:147], v[148:151], v[34:37]
	ds_read_b128 v[148:151], v135 offset:16128
	v_fma_f32 v76, -v50, v50, 1.0
	v_max_f32_e32 v76, 0, v76
	v_sqrt_f32_e32 v136, v76
	ds_read2_b32 v[76:77], v0 offset1:16
	s_waitcnt lgkmcnt(1)
	v_mfma_f32_16x16x32_bf16 v[26:29], v[26:29], v[148:151], 0
	ds_read_b128 v[148:151], v135 offset:16192
	v_mul_f32_e32 v46, v46, v136
	ds_write_b32 v0, v50 offset:32768
	s_waitcnt lgkmcnt(2)
; __device__ __forceinline__ float frcp(float x) { return __builtin_amdgcn_rcpf(x); }
; __device__ __forceinline__ void lru_item(const Args& A, Frame& F, int l, int it) {
;     ...
; #pragma unroll
;             for (int nt = 0; nt < 4; ++nt)
; #pragma unroll
;                 for (int r = 0; r < 4; ++r) {
;                     const int si = 16 * w + 4 * fq + r, ch = 16 * nt + fr;
;                     const float d0 = 1.f + __builtin_amdgcn_exp2f(fminf((gacc[nt][r] + bgr[nt]) * -1.4426950408889634f, 60.f));
;                     const float d1 = 1.f + __builtin_amdgcn_exp2f(fminf((gacc[nt + 4][r] + bgi[nt]) * -1.4426950408889634f, 60.f));
;                     const float rr = frcp(d0 * d1);
;                     const float rg = rr * d1, ig = rr * d0;
;                     const float av = __builtin_amdgcn_exp2f(rg * spl[nt]);
;                     const float mult = __builtin_amdgcn_sqrtf(fmaxf(1.f - av * av, 0.f));
;                     const float uu = us[si * 64 + ch];
;                     as[si * 64 + ch] = av;
;                     us[si * 64 + ch] = mult * ig * uu;
;                 }
	v_mul_f32_e32 v46, v76, v46
	ds_write_b32 v0, v46
	v_add_f32_e32 v46, v55, v47
	v_add_f32_e32 v47, v83, v51
	v_mul_f32_e32 v46, 0xbfb8aa3b, v46
	v_mul_f32_e32 v47, 0xbfb8aa3b, v47
	v_min_f32_e32 v46, 0x42700000, v46
	v_min_f32_e32 v47, 0x42700000, v47
	v_exp_f32_e32 v46, v46
	v_exp_f32_e32 v47, v47
	v_add_f32_e32 v42, v84, v42
	v_mul_f32_e32 v42, 0xbfb8aa3b, v42
	v_add_f32_e32 v46, 1.0, v46
	v_add_f32_e32 v47, 1.0, v47
	v_mul_f32_e32 v50, v46, v47
	v_rcp_f32_e32 v50, v50
	v_min_f32_e32 v42, 0x42700000, v42
	v_exp_f32_e32 v42, v42
	v_add_f32_e32 v34, v85, v34
	v_mul_f32_e32 v47, v47, v50
	v_mul_f32_e32 v50, v46, v50
	v_mul_f32_e32 v46, v80, v47
	v_exp_f32_e32 v51, v46
	v_add_f32_e32 v42, 1.0, v42
	v_mul_f32_e32 v34, 0xbfb8aa3b, v34
	v_min_f32_e32 v34, 0x42700000, v34
	v_fma_f32 v46, -v51, v51, 1.0
	v_max_f32_e32 v46, 0, v46
	v_sqrt_f32_e32 v76, v46
	ds_read2st64_b32 v[46:47], v0 offset0:1 offset1:2
	v_exp_f32_e32 v30, v30
	v_exp_f32_e32 v34, v34
	v_mul_f32_e32 v50, v50, v76
	v_add_f32_e32 v32, v78, v32
	s_waitcnt lgkmcnt(0)
	v_mul_f32_e32 v46, v46, v50
	v_add_f32_e32 v50, v83, v52
	v_mul_f32_e32 v50, 0xbfb8aa3b, v50
	v_min_f32_e32 v50, 0x42700000, v50
	v_exp_f32_e32 v50, v50
	v_add_f32_e32 v30, 1.0, v30
	v_add_f32_e32 v34, 1.0, v34
	v_mul_f32_e32 v32, 0xbfb8aa3b, v32
	v_add_f32_e32 v50, 1.0, v50
	v_mul_f32_e32 v52, v48, v50
	v_rcp_f32_e32 v52, v52
	v_min_f32_e32 v32, 0x42700000, v32
	v_exp_f32_e32 v32, v32
	v_mfma_f32_16x16x32_bf16 v[26:29], v[144:147], v[148:151], v[26:29]
	v_mul_f32_e32 v50, v50, v52
	v_mul_f32_e32 v50, v80, v50
	v_exp_f32_e32 v50, v50
	v_mul_f32_e32 v48, v48, v52
	v_add_f32_e32 v32, 1.0, v32
	v_add_f32_e32 v22, v79, v22
	v_fma_f32 v52, -v50, v50, 1.0
	v_max_f32_e32 v52, 0, v52
	v_sqrt_f32_e32 v52, v52
	ds_write2st64_b32 v0, v51, v50 offset0:129 offset1:130
	v_add_f32_e32 v26, v86, v26
	v_mul_f32_e32 v22, 0xbfb8aa3b, v22
	v_mul_f32_e32 v48, v48, v52
	v_mul_f32_e32 v47, v48, v47
	ds_write2st64_b32 v0, v46, v47 offset0:1 offset1:2
	v_add_f32_e32 v46, v55, v49
	v_add_f32_e32 v47, v83, v53
	v_mul_f32_e32 v46, 0xbfb8aa3b, v46
	v_mul_f32_e32 v47, 0xbfb8aa3b, v47
	v_min_f32_e32 v46, 0x42700000, v46
	v_min_f32_e32 v47, 0x42700000, v47
	v_exp_f32_e32 v46, v46
	v_exp_f32_e32 v47, v47
	ds_read_b32 v49, v0 offset:768
	v_mul_f32_e32 v26, 0xbfb8aa3b, v26
	v_add_f32_e32 v46, 1.0, v46
	v_add_f32_e32 v47, 1.0, v47
	v_mul_f32_e32 v48, v46, v47
	v_rcp_f32_e32 v48, v48
	v_min_f32_e32 v22, 0x42700000, v22
	v_min_f32_e32 v26, 0x42700000, v26
	v_exp_f32_e32 v22, v22
	v_mul_f32_e32 v47, v47, v48
	v_mul_f32_e32 v47, v80, v47
	v_exp_f32_e32 v47, v47
	v_mul_f32_e32 v46, v46, v48
	v_exp_f32_e32 v26, v26
	v_add_f32_e32 v22, 1.0, v22
	v_fma_f32 v48, -v47, v47, 1.0
	v_max_f32_e32 v48, 0, v48
	v_sqrt_f32_e32 v48, v48
	ds_write_b32 v0, v47 offset:33536
	v_add_f32_e32 v26, 1.0, v26
	v_add_f32_e32 v24, v79, v24
	v_mul_f32_e32 v46, v46, v48
	s_waitcnt lgkmcnt(1)
	v_mul_f32_e32 v46, v46, v49
	ds_write_b32 v0, v46 offset:768
	v_mul_f32_e32 v46, v38, v42
	v_rcp_f32_e32 v46, v46
	v_mul_f32_e32 v24, 0xbfb8aa3b, v24
	v_min_f32_e32 v24, 0x42700000, v24
	v_exp_f32_e32 v24, v24
	v_mul_f32_e32 v42, v42, v46
	v_mul_f32_e32 v42, v81, v42
	v_exp_f32_e32 v42, v42
	v_mul_f32_e32 v38, v38, v46
	v_add_f32_e32 v24, 1.0, v24
	v_fma_f32 v46, -v42, v42, 1.0
	v_max_f32_e32 v46, 0, v46
	v_sqrt_f32_e32 v46, v46
	ds_write_b32 v0, v42 offset:32832
	v_mul_f32_e32 v38, v38, v46
	v_mul_f32_e32 v38, v38, v77
	ds_write_b32 v0, v38 offset:64
	v_add_f32_e32 v38, v59, v39
	v_add_f32_e32 v39, v84, v43
	v_mul_f32_e32 v38, 0xbfb8aa3b, v38
	v_mul_f32_e32 v39, 0xbfb8aa3b, v39
	v_min_f32_e32 v38, 0x42700000, v38
	v_min_f32_e32 v39, 0x42700000, v39
	v_exp_f32_e32 v38, v38
	v_exp_f32_e32 v39, v39
	v_add_f32_e32 v38, 1.0, v38
	v_add_f32_e32 v39, 1.0, v39
	v_mul_f32_e32 v42, v38, v39
	v_rcp_f32_e32 v42, v42
	s_nop 0
	v_mul_f32_e32 v39, v39, v42
	v_mul_f32_e32 v42, v38, v42
	v_mul_f32_e32 v38, v81, v39
	v_exp_f32_e32 v43, v38
	s_nop 0
	v_fma_f32 v38, -v43, v43, 1.0
	v_max_f32_e32 v38, 0, v38
	v_sqrt_f32_e32 v46, v38
	ds_read2st64_b32 v[38:39], v93 offset0:1 offset1:2
	v_mul_f32_e32 v42, v42, v46
	s_waitcnt lgkmcnt(0)
	v_mul_f32_e32 v38, v42, v38
	v_add_f32_e32 v42, v84, v44
	v_mul_f32_e32 v42, 0xbfb8aa3b, v42
	v_min_f32_e32 v42, 0x42700000, v42
	v_exp_f32_e32 v42, v42
	s_nop 0
	v_add_f32_e32 v42, 1.0, v42
	v_mul_f32_e32 v44, v40, v42
	v_rcp_f32_e32 v44, v44
	s_nop 0
	v_mul_f32_e32 v42, v42, v44
	v_mul_f32_e32 v42, v81, v42
	v_exp_f32_e32 v42, v42
	v_mul_f32_e32 v40, v40, v44
	v_fma_f32 v44, -v42, v42, 1.0
	v_max_f32_e32 v44, 0, v44
	v_sqrt_f32_e32 v44, v44
	s_nop 0
	v_mul_f32_e32 v40, v40, v44
	v_mul_f32_e32 v39, v40, v39
	ds_write2st64_b32 v93, v38, v39 offset0:1 offset1:2
	v_add_f32_e32 v38, v59, v41
	v_add_f32_e32 v39, v84, v45
	v_mul_f32_e32 v38, 0xbfb8aa3b, v38
	v_mul_f32_e32 v39, 0xbfb8aa3b, v39
	v_min_f32_e32 v38, 0x42700000, v38
	v_min_f32_e32 v39, 0x42700000, v39
	v_exp_f32_e32 v38, v38
	v_exp_f32_e32 v39, v39
	ds_read_b32 v41, v93 offset:768
	v_add_f32_e32 v38, 1.0, v38
	v_add_f32_e32 v39, 1.0, v39
	v_mul_f32_e32 v40, v38, v39
	v_rcp_f32_e32 v40, v40
	s_nop 0
	v_mul_f32_e32 v39, v39, v40
	v_mul_f32_e32 v39, v81, v39
	v_exp_f32_e32 v39, v39
	v_mul_f32_e32 v38, v38, v40
	v_fma_f32 v40, -v39, v39, 1.0
	v_max_f32_e32 v40, 0, v40
	v_sqrt_f32_e32 v40, v40
	ds_write2st64_b32 v93, v42, v39 offset0:130 offset1:131
	v_mul_f32_e32 v38, v38, v40
	s_waitcnt lgkmcnt(1)
; __device__ __forceinline__ float frcp(float x) { return __builtin_amdgcn_rcpf(x); }
; #define ST_LOAD(KS, VS, mc_) do { const int _p0 = 128 * (mc_); _Pragma("unroll") for (int ks = 0; ks < 4; ++ks) { VS[ks] = *(const bf16x8*)(vbase + _p0 + 32 * ks + 8 * fq); \
;         _Pragma("unroll") for (int t = 0; t < 2; ++t) KS[ks][t] = *(const bf16x8*)(kbase + (size_t)(16 * t) * TB + _p0 + 32 * ks + 8 * fq); } } while (0)
; #define ST_STORE(mc_) do { bf16_t* stp = WSB(WS_ST) + ((((size_t)(b * NH + h) * 2 + dir) * NCH + (mc_)) * DV + dvrow) * DK + 32 * dkh + 4 * fq; \
;         _Pragma("unroll") for (int t = 0; t < 2; ++t) { u32x2 o; o.x = pk2(acc[t][0], acc[t][1]); o.y = pk2(acc[t][2], acc[t][3]); *(u32x2*)(stp + 16 * t) = o; } } while (0)
; __device__ __forceinline__ void ret_state_item(const Args& A, Frame& F, int l, int it) {
;     ...
;     ST_LOAD(ka, va, ST_MC(0));
;     for (int s2 = 0; s2 < NCH; s2 += 2) {
;         ST_STORE(ST_MC(s2));
;         { const int sn = s2 + 1 < NCH - 1 ? s2 + 1 : NCH - 2; ST_LOAD(kb2, vb2, ST_MC(sn)); }
;         ST_COMPUTE(ka, va);
;         ST_STORE(ST_MC(s2 + 1));
;         if (s2 + 1 == NCH - 1) break;
; __device__ __forceinline__ void lru_item(const Args& A, Frame& F, int l, int it) {
;     ...
;             for (int nt = 0; nt < 4; ++nt)
; #pragma unroll
;                 for (int r = 0; r < 4; ++r) {
;                     const int si = 16 * w + 4 * fq + r, ch = 16 * nt + fr;
;                     const float d0 = 1.f + __builtin_amdgcn_exp2f(fminf((gacc[nt][r] + bgr[nt]) * -1.4426950408889634f, 60.f));
;                     const float d1 = 1.f + __builtin_amdgcn_exp2f(fminf((gacc[nt + 4][r] + bgi[nt]) * -1.4426950408889634f, 60.f));
;                     const float rr = frcp(d0 * d1);
;                     const float rg = rr * d1, ig = rr * d0;
;                     const float av = __builtin_amdgcn_exp2f(rg * spl[nt]);
;                     const float mult = __builtin_amdgcn_sqrtf(fmaxf(1.f - av * av, 0.f));
;                     const float uu = us[si * 64 + ch];
;                     as[si * 64 + ch] = av;
;                     us[si * 64 + ch] = mult * ig * uu;
;                 }
	v_mul_f32_e32 v38, v38, v41
	ds_write2st64_b32 v93, v38, v43 offset0:3 offset1:129
	v_mul_f32_e32 v38, v30, v34
	v_rcp_f32_e32 v38, v38
	ds_read_b32 v39, v0 offset:128
	v_mul_f32_e32 v34, v34, v38
	v_mul_f32_e32 v34, v82, v34
	v_exp_f32_e32 v34, v34
	v_mul_f32_e32 v30, v30, v38
	v_fma_f32 v38, -v34, v34, 1.0
	v_max_f32_e32 v38, 0, v38
	v_sqrt_f32_e32 v38, v38
	ds_write_b32 v0, v34 offset:32896
	v_mul_f32_e32 v30, v30, v38
	s_waitcnt lgkmcnt(1)
	v_mul_f32_e32 v30, v30, v39
	ds_write_b32 v0, v30 offset:128
	v_add_f32_e32 v30, v78, v31
	v_add_f32_e32 v31, v85, v35
	v_mul_f32_e32 v30, 0xbfb8aa3b, v30
	v_mul_f32_e32 v31, 0xbfb8aa3b, v31
	v_min_f32_e32 v30, 0x42700000, v30
	v_min_f32_e32 v31, 0x42700000, v31
	v_exp_f32_e32 v30, v30
	v_exp_f32_e32 v31, v31
	v_add_f32_e32 v30, 1.0, v30
	v_add_f32_e32 v31, 1.0, v31
	v_mul_f32_e32 v34, v30, v31
	v_rcp_f32_e32 v34, v34
	s_nop 0
	v_mul_f32_e32 v31, v31, v34
	v_mul_f32_e32 v34, v30, v34
	v_mul_f32_e32 v30, v82, v31
	v_exp_f32_e32 v35, v30
	s_nop 0
	v_fma_f32 v30, -v35, v35, 1.0
	v_max_f32_e32 v30, 0, v30
	v_sqrt_f32_e32 v38, v30
	ds_read2st64_b32 v[30:31], v94 offset0:1 offset1:2
	v_mul_f32_e32 v34, v34, v38
	s_waitcnt lgkmcnt(0)
	v_mul_f32_e32 v30, v34, v30
	v_add_f32_e32 v34, v85, v36
	v_mul_f32_e32 v34, 0xbfb8aa3b, v34
	v_min_f32_e32 v34, 0x42700000, v34
	v_exp_f32_e32 v34, v34
	s_nop 0
	v_add_f32_e32 v34, 1.0, v34
	v_mul_f32_e32 v36, v32, v34
	v_rcp_f32_e32 v36, v36
	s_nop 0
	v_mul_f32_e32 v34, v34, v36
	v_mul_f32_e32 v34, v82, v34
	v_exp_f32_e32 v34, v34
	v_mul_f32_e32 v32, v32, v36
	v_fma_f32 v36, -v34, v34, 1.0
	v_max_f32_e32 v36, 0, v36
	v_sqrt_f32_e32 v36, v36
	s_nop 0
	v_mul_f32_e32 v32, v32, v36
	v_mul_f32_e32 v31, v32, v31
	ds_write2st64_b32 v94, v30, v31 offset0:1 offset1:2
	v_add_f32_e32 v30, v78, v33
	v_add_f32_e32 v31, v85, v37
	v_mul_f32_e32 v30, 0xbfb8aa3b, v30
	v_mul_f32_e32 v31, 0xbfb8aa3b, v31
	v_min_f32_e32 v30, 0x42700000, v30
	v_min_f32_e32 v31, 0x42700000, v31
	v_exp_f32_e32 v30, v30
	v_exp_f32_e32 v31, v31
	ds_read_b32 v33, v94 offset:768
	v_add_f32_e32 v30, 1.0, v30
	v_add_f32_e32 v31, 1.0, v31
	v_mul_f32_e32 v32, v30, v31
	v_rcp_f32_e32 v32, v32
	s_nop 0
	v_mul_f32_e32 v31, v31, v32
	v_mul_f32_e32 v31, v82, v31
	v_exp_f32_e32 v31, v31
	v_mul_f32_e32 v30, v30, v32
	v_fma_f32 v32, -v31, v31, 1.0
	v_max_f32_e32 v32, 0, v32
	v_sqrt_f32_e32 v32, v32
	ds_write2st64_b32 v94, v34, v31 offset0:130 offset1:131
	v_mul_f32_e32 v30, v30, v32
	s_waitcnt lgkmcnt(1)
	v_mul_f32_e32 v30, v30, v33
	ds_write2st64_b32 v94, v30, v35 offset0:3 offset1:129
	v_mul_f32_e32 v30, v22, v26
	v_rcp_f32_e32 v30, v30
	ds_read_b32 v31, v0 offset:192
	v_mul_f32_e32 v26, v26, v30
	v_mul_f32_e32 v26, v87, v26
	v_exp_f32_e32 v26, v26
	v_mul_f32_e32 v22, v22, v30
	v_fma_f32 v30, -v26, v26, 1.0
	v_max_f32_e32 v30, 0, v30
	v_sqrt_f32_e32 v30, v30
	ds_write_b32 v0, v26 offset:32960
	v_mul_f32_e32 v22, v22, v30
	s_waitcnt lgkmcnt(1)
	v_mul_f32_e32 v22, v22, v31
	ds_write_b32 v0, v22 offset:192
	v_add_f32_e32 v22, v79, v23
	v_add_f32_e32 v23, v86, v27
	v_mul_f32_e32 v22, 0xbfb8aa3b, v22
	v_mul_f32_e32 v23, 0xbfb8aa3b, v23
	v_min_f32_e32 v22, 0x42700000, v22
	v_min_f32_e32 v23, 0x42700000, v23
	v_exp_f32_e32 v22, v22
	v_exp_f32_e32 v23, v23
	v_add_f32_e32 v22, 1.0, v22
	v_add_f32_e32 v23, 1.0, v23
	v_mul_f32_e32 v26, v22, v23
	v_rcp_f32_e32 v26, v26
	s_nop 0
	v_mul_f32_e32 v23, v23, v26
	v_mul_f32_e32 v26, v22, v26
	v_mul_f32_e32 v22, v87, v23
	v_exp_f32_e32 v27, v22
	s_nop 0
	v_fma_f32 v22, -v27, v27, 1.0
	v_max_f32_e32 v22, 0, v22
	v_sqrt_f32_e32 v30, v22
	ds_read2st64_b32 v[22:23], v95 offset0:1 offset1:2
	v_mul_f32_e32 v26, v26, v30
	s_waitcnt lgkmcnt(0)
	v_mul_f32_e32 v22, v26, v22
	v_add_f32_e32 v26, v86, v28
	v_mul_f32_e32 v26, 0xbfb8aa3b, v26
	v_min_f32_e32 v26, 0x42700000, v26
	v_exp_f32_e32 v26, v26
	s_nop 0
	v_add_f32_e32 v26, 1.0, v26
	v_mul_f32_e32 v28, v24, v26
	v_rcp_f32_e32 v28, v28
	s_nop 0
	v_mul_f32_e32 v26, v26, v28
	v_mul_f32_e32 v26, v87, v26
	v_exp_f32_e32 v26, v26
	v_mul_f32_e32 v24, v24, v28
	v_fma_f32 v28, -v26, v26, 1.0
	v_max_f32_e32 v28, 0, v28
	v_sqrt_f32_e32 v28, v28
	s_nop 0
	v_mul_f32_e32 v24, v24, v28
	v_mul_f32_e32 v23, v24, v23
	ds_write2st64_b32 v95, v22, v23 offset0:1 offset1:2
	v_add_f32_e32 v22, v79, v25
	v_add_f32_e32 v23, v86, v29
	v_mul_f32_e32 v22, 0xbfb8aa3b, v22
	v_mul_f32_e32 v23, 0xbfb8aa3b, v23
	v_min_f32_e32 v22, 0x42700000, v22
	v_min_f32_e32 v23, 0x42700000, v23
	v_exp_f32_e32 v22, v22
	v_exp_f32_e32 v23, v23
	ds_read_b32 v25, v95 offset:768
	v_add_f32_e32 v22, 1.0, v22
	v_add_f32_e32 v23, 1.0, v23
	v_mul_f32_e32 v24, v22, v23
	v_rcp_f32_e32 v24, v24
	s_nop 0
	v_mul_f32_e32 v23, v23, v24
	v_mul_f32_e32 v23, v87, v23
	v_exp_f32_e32 v23, v23
	v_mul_f32_e32 v22, v22, v24
	v_fma_f32 v24, -v23, v23, 1.0
	v_max_f32_e32 v24, 0, v24
	v_sqrt_f32_e32 v24, v24
	ds_write2st64_b32 v95, v26, v23 offset0:130 offset1:131
	v_mul_f32_e32 v22, v22, v24
	s_waitcnt lgkmcnt(1)
	v_mul_f32_e32 v22, v22, v25
	ds_write2st64_b32 v95, v22, v27 offset0:3 offset1:129
	s_waitcnt lgkmcnt(0)
	s_add_i32 s100, s45, -1
	s_bfe_u32 s101, s37, 0x10001
	s_cmp_eq_u32 s101, 0
	s_cbranch_scc1 .Lfz_mc_st
	s_sub_i32 s101, 19, s100
	s_cmp_lt_u32 s100, 2
	s_cbranch_scc0 .Lfz_mc1_st
	s_sub_i32 s101, 1, s100

; #define ST_LOAD(KS, VS, mc_) do { const int _p0 = 128 * (mc_); _Pragma("unroll") for (int ks = 0; ks < 4; ++ks) { VS[ks] = *(const bf16x8*)(vbase + _p0 + 32 * ks + 8 * fq); \
;         _Pragma("unroll") for (int t = 0; t < 2; ++t) KS[ks][t] = *(const bf16x8*)(kbase + (size_t)(16 * t) * TB + _p0 + 32 * ks + 8 * fq); } } while (0)
; #define ST_STORE(mc_) do { bf16_t* stp = WSB(WS_ST) + ((((size_t)(b * NH + h) * 2 + dir) * NCH + (mc_)) * DV + dvrow) * DK + 32 * dkh + 4 * fq; \
;         _Pragma("unroll") for (int t = 0; t < 2; ++t) { u32x2 o; o.x = pk2(acc[t][0], acc[t][1]); o.y = pk2(acc[t][2], acc[t][3]); *(u32x2*)(stp + 16 * t) = o; } } while (0)
; #define ST_COMPUTE(KS, VS) do { acc[0] *= cdec; acc[1] *= cdec; _Pragma("unroll") for (int ks = 0; ks < 4; ++ks) { const bf16x8 bv = scale8(VS[ks], dec[ks]); \
;         _Pragma("unroll") for (int t = 0; t < 2; ++t) acc[t] = __builtin_amdgcn_mfma_f32_16x16x32_bf16(KS[ks][t], bv, acc[t], 0, 0, 0); } } while (0)
; __device__ __forceinline__ void ret_state_item(const Args& A, Frame& F, int l, int it) {
;     ...
;     ST_LOAD(ka, va, ST_MC(0));
;     for (int s2 = 0; s2 < NCH; s2 += 2) {
;         ST_STORE(ST_MC(s2));
;         { const int sn = s2 + 1 < NCH - 1 ? s2 + 1 : NCH - 2; ST_LOAD(kb2, vb2, ST_MC(sn)); }
;         ST_COMPUTE(ka, va);
;         ST_STORE(ST_MC(s2 + 1));
;         if (s2 + 1 == NCH - 1) break;
;         { const int sn = s2 + 2 < NCH - 1 ? s2 + 2 : NCH - 2; ST_LOAD(ka, va, ST_MC(sn)); }
;         ST_COMPUTE(kb2, vb2);
.Lfz_mc_st:
	s_lshl_b32 s101, s100, 14
	s_add_u32 s98, s30, 0x1b0c8000
	s_addc_u32 s99, s31, 0
	s_add_u32 s98, s98, s101
	s_addc_u32 s99, s99, 0
	v_cvt_pk_bf16_f32 v250, v160, v161
	v_cvt_pk_bf16_f32 v251, v162, v163
	v_cvt_pk_bf16_f32 v252, v164, v165
	v_cvt_pk_bf16_f32 v253, v166, v167
	s_nop 1
	v_permlane16_swap_b32 v250, v252
	v_permlane16_swap_b32 v251, v253
	global_store_dwordx4 v243, v[250:253], s[98:99]
	s_waitcnt vmcnt(8)
	s_cmp_eq_u32 s45, 18
	s_cbranch_scc1 .Lfz_skip
	v_pk_mul_f32 v[160:161], v[160:161], v[168:169] op_sel_hi:[1,0]
	v_pk_mul_f32 v[162:163], v[162:163], v[168:169] op_sel_hi:[1,0]
	v_pk_mul_f32 v[164:165], v[164:165], v[168:169] op_sel_hi:[1,0]
	v_pk_mul_f32 v[166:167], v[166:167], v[168:169] op_sel_hi:[1,0]
	v_lshlrev_b32_e32 v250, 16, v98
	v_and_b32_e32 v251, 0xffff0000, v98
	v_pk_mul_f32 v[250:251], v[250:251], v[152:153]
	v_cvt_pk_bf16_f32 v98, v250, v251
	v_lshlrev_b32_e32 v252, 16, v99
	v_and_b32_e32 v253, 0xffff0000, v99
	v_pk_mul_f32 v[252:253], v[252:253], v[154:155]
	v_cvt_pk_bf16_f32 v99, v252, v253
	v_lshlrev_b32_e32 v250, 16, v100
	v_and_b32_e32 v251, 0xffff0000, v100
	v_pk_mul_f32 v[250:251], v[250:251], v[156:157]
	v_cvt_pk_bf16_f32 v100, v250, v251
	v_lshlrev_b32_e32 v252, 16, v101
	v_and_b32_e32 v253, 0xffff0000, v101
	v_pk_mul_f32 v[252:253], v[252:253], v[158:159]
	v_cvt_pk_bf16_f32 v101, v252, v253
	v_lshlrev_b32_e32 v250, 16, v104
	v_and_b32_e32 v251, 0xffff0000, v104
	v_pk_mul_f32 v[250:251], v[250:251], v[152:153]
	v_pk_mul_f32 v[250:251], v[250:251], v[244:245] op_sel_hi:[1,0]
	v_cvt_pk_bf16_f32 v104, v250, v251
	v_lshlrev_b32_e32 v252, 16, v105
	v_and_b32_e32 v253, 0xffff0000, v105
	v_pk_mul_f32 v[252:253], v[252:253], v[154:155]
	v_pk_mul_f32 v[252:253], v[252:253], v[244:245] op_sel_hi:[1,0]
	v_cvt_pk_bf16_f32 v105, v252, v253
	v_lshlrev_b32_e32 v250, 16, v106
	v_and_b32_e32 v251, 0xffff0000, v106
	v_pk_mul_f32 v[250:251], v[250:251], v[156:157]
	v_pk_mul_f32 v[250:251], v[250:251], v[244:245] op_sel_hi:[1,0]
	v_cvt_pk_bf16_f32 v106, v250, v251
	v_lshlrev_b32_e32 v252, 16, v107
	v_and_b32_e32 v253, 0xffff0000, v107
	v_pk_mul_f32 v[252:253], v[252:253], v[158:159]
	v_pk_mul_f32 v[252:253], v[252:253], v[244:245] op_sel_hi:[1,0]
	v_cvt_pk_bf16_f32 v107, v252, v253
	v_lshlrev_b32_e32 v250, 16, v108
	v_and_b32_e32 v251, 0xffff0000, v108
	v_pk_mul_f32 v[250:251], v[250:251], v[152:153]
	v_pk_mul_f32 v[250:251], v[250:251], v[246:247] op_sel_hi:[1,0]
	v_cvt_pk_bf16_f32 v108, v250, v251
	v_lshlrev_b32_e32 v252, 16, v109
	v_and_b32_e32 v253, 0xffff0000, v109
	v_pk_mul_f32 v[252:253], v[252:253], v[154:155]
	v_pk_mul_f32 v[252:253], v[252:253], v[246:247] op_sel_hi:[1,0]
	v_cvt_pk_bf16_f32 v109, v252, v253
	v_lshlrev_b32_e32 v250, 16, v110
	v_and_b32_e32 v251, 0xffff0000, v110
	v_pk_mul_f32 v[250:251], v[250:251], v[156:157]
	v_pk_mul_f32 v[250:251], v[250:251], v[246:247] op_sel_hi:[1,0]
	v_cvt_pk_bf16_f32 v110, v250, v251
	v_lshlrev_b32_e32 v252, 16, v111
	v_and_b32_e32 v253, 0xffff0000, v111
	v_pk_mul_f32 v[252:253], v[252:253], v[158:159]
	v_pk_mul_f32 v[252:253], v[252:253], v[246:247] op_sel_hi:[1,0]
	v_cvt_pk_bf16_f32 v111, v252, v253
	v_lshlrev_b32_e32 v250, 16, v112
	v_and_b32_e32 v251, 0xffff0000, v112
	v_pk_mul_f32 v[250:251], v[250:251], v[152:153]
	v_pk_mul_f32 v[250:251], v[250:251], v[248:249] op_sel_hi:[1,0]
	v_cvt_pk_bf16_f32 v112, v250, v251
	v_lshlrev_b32_e32 v252, 16, v113
	v_and_b32_e32 v253, 0xffff0000, v113
	v_pk_mul_f32 v[252:253], v[252:253], v[154:155]
	v_pk_mul_f32 v[252:253], v[252:253], v[248:249] op_sel_hi:[1,0]
	v_cvt_pk_bf16_f32 v113, v252, v253
	v_lshlrev_b32_e32 v250, 16, v114
	v_and_b32_e32 v251, 0xffff0000, v114
	v_pk_mul_f32 v[250:251], v[250:251], v[156:157]
	v_pk_mul_f32 v[250:251], v[250:251], v[248:249] op_sel_hi:[1,0]
	v_cvt_pk_bf16_f32 v114, v250, v251
	v_lshlrev_b32_e32 v252, 16, v115
	v_and_b32_e32 v253, 0xffff0000, v115
	v_pk_mul_f32 v[252:253], v[252:253], v[158:159]
	v_pk_mul_f32 v[252:253], v[252:253], v[248:249] op_sel_hi:[1,0]
	v_cvt_pk_bf16_f32 v115, v252, v253
	s_nop 1
	v_mfma_f32_16x16x32_bf16 v[160:163], v[116:119], v[98:101], v[160:163]
	v_mfma_f32_16x16x32_bf16 v[164:167], v[194:197], v[98:101], v[164:167]
	v_mfma_f32_16x16x32_bf16 v[160:163], v[120:123], v[104:107], v[160:163]
	v_mfma_f32_16x16x32_bf16 v[164:167], v[198:201], v[104:107], v[164:167]
	v_mfma_f32_16x16x32_bf16 v[160:163], v[124:127], v[108:111], v[160:163]
	v_mfma_f32_16x16x32_bf16 v[164:167], v[202:205], v[108:111], v[164:167]
	v_mfma_f32_16x16x32_bf16 v[160:163], v[190:193], v[112:115], v[160:163]
	v_mfma_f32_16x16x32_bf16 v[164:167], v[206:209], v[112:115], v[164:167]
	s_min_u32 s100, s45, 16
	s_bfe_u32 s101, s37, 0x10001
	s_cmp_eq_u32 s101, 0
	s_cbranch_scc1 .Lfz_mc_e
	s_sub_i32 s101, 19, s100
	s_cmp_lt_u32 s100, 2
	s_cbranch_scc0 .Lfz_mc1_e
	s_sub_i32 s101, 1, s100
